# adds SwiGLU epilogue rowss prefetch one tile ahead (P7,P13) on top of attention wait fixes
# speedup vs baseline: 1.0037x; 1.0037x over previous
.LBB0_549:
	s_lshl_b32 s12, s12, 5
	s_and_b32 s17, s12, 0x60
	s_mov_b64 s[12:13], 0x80
	s_add_i32 m0, s25, 0x18000
	v_lshl_add_u64 v[6:7], v[6:7], 0, s[12:13]
	s_lshl_b32 s16, s7, 13
	s_lshl_b32 s18, s17, 7
	s_waitcnt vmcnt(2)
	s_barrier
	global_load_lds_dwordx4 v[6:7], off
	v_lshl_add_u64 v[4:5], v[4:5], 0, s[12:13]
	s_add_i32 m0, s25, 0x1a000
	s_add_i32 s42, s25, 0x8000
	s_add_i32 s43, s25, 0xa000
	global_load_lds_dwordx4 v[4:5], off
	v_lshl_add_u64 v[0:1], v[0:1], 0, s[12:13]
	s_mov_b32 m0, s42
	s_add_u32 s14, s30, 0x40080
	global_load_lds_dwordx4 v[0:1], off
	v_lshl_add_u64 v[0:1], v[2:3], 0, s[12:13]
	s_mov_b32 m0, s43
	s_addc_u32 s15, s31, 0
	global_load_lds_dwordx4 v[0:1], off
	s_add_i32 m0, s25, 0x1c000
	v_lshl_add_u64 v[0:1], s[14:15], 0, v[132:133]
	global_load_lds_dwordx4 v[0:1], off
	v_lshl_add_u64 v[0:1], s[14:15], 0, v[128:129]
	s_add_i32 m0, s25, 0x1e000
	s_cmpk_lt_u32 s6, 0x100
	global_load_lds_dwordx4 v[0:1], off
	v_lshrrev_b32_e32 v1, 1, v9
	v_and_b32_e32 v1, 24, v1
	v_and_b32_e32 v0, 15, v9
	v_lshlrev_b32_e32 v2, 1, v1
	v_lshl_or_b32 v146, s7, 6, v0
	v_lshl_or_b32 v0, v0, 6, v2
	v_lshlrev_b32_e32 v2, 2, v9
	v_and_b32_e32 v2, 32, v2
	v_bitop3_b32 v3, v0, s16, v2 bitop3:0xde
	v_bitop3_b32 v147, v0, s18, v2 bitop3:0xde
	v_lshlrev_b32_e32 v0, 14, v13
	v_and_b32_e32 v0, 0xffff8000, v0
	v_or_b32_e32 v148, s17, v1
	v_lshl_add_u32 v0, v12, 11, v0
	v_and_b32_e32 v1, 1, v13
	v_lshl_or_b32 v0, v1, 6, v0
	v_lshl_add_u32 v136, v14, 1, v0
	v_lshlrev_b32_e32 v0, 14, v8
	v_and_b32_e32 v0, 0xffff8000, v0
	s_waitcnt vmcnt(6)
	v_lshl_add_u32 v0, v10, 11, v0
	v_and_b32_e32 v1, 1, v8
	s_cselect_b64 s[14:15], -1, 0
	v_lshl_or_b32 v0, v1, 6, v0
	s_add_i32 s48, 0, 0x10000
	s_add_i32 s49, 0, 0x14000
	s_ashr_i32 s46, s52, 31
	s_mov_b32 s47, s52
	v_mov_b32_e32 v137, v133
	v_lshl_add_u32 v138, v11, 1, v0
	v_mov_b32_e32 v139, v133
	v_mov_b64_e32 v[140:141], 0xb00
	v_mov_b64_e32 v[142:143], 0xaff
	v_add_u32_e32 v149, s48, v147
	v_add_u32_e32 v150, s49, v147
	v_add_u32_e32 v151, 0, v3
	v_mov_b32_e32 v152, 0x358637bd
	s_movk_i32 s50, 0x1600
	s_barrier
	v_lshl_add_u32 v238, s26, 8, v146
	v_ashrrev_i32_e32 v239, 31, v238
	v_lshl_add_u64 v[238:239], v[238:239], 2, s[8:9]
	global_load_dword v230, v[238:239], off sc1
	global_load_dword v231, v[238:239], off offset:64 sc1
	global_load_dword v232, v[238:239], off offset:128 sc1
	global_load_dword v233, v[238:239], off offset:192 sc1
	global_load_dword v234, v[238:239], off offset:512 sc1
	global_load_dword v235, v[238:239], off offset:576 sc1
	global_load_dword v236, v[238:239], off offset:640 sc1
	global_load_dword v237, v[238:239], off offset:704 sc1
	s_branch .LBB0_552

.LBB0_558:
	v_lshl_add_u32 v144, s26, 8, v146
	v_mov_b32_e32 v145, v230
	v_mov_b32_e32 v153, v231
	v_lshl_or_b32 v156, s24, 7, v148
	v_ashrrev_i32_e32 v157, 31, v156
	v_mul_f32_e32 v162, v108, v104
	v_mul_f32_e32 v163, v109, v105
	v_lshlrev_b64 v[104:105], 1, v[156:157]
	v_mov_b32_e32 v156, v232
	v_mov_b32_e32 v157, v233
	v_mov_b32_e32 v165, v234
	v_mov_b32_e32 v166, v235
	v_mov_b32_e32 v167, v236
	v_mul_f32_e32 v164, v110, v106
	v_mov_b32_e32 v106, v237
	s_and_b64 s[98:99], s[6:7], exec
	s_cselect_b32 s98, s18, s26
	v_lshl_add_u32 v238, s98, 8, v146
	v_ashrrev_i32_e32 v239, 31, v238
	v_lshl_add_u64 v[238:239], v[238:239], 2, s[8:9]
	global_load_dword v230, v[238:239], off sc1
	global_load_dword v231, v[238:239], off offset:64 sc1
	global_load_dword v232, v[238:239], off offset:128 sc1
	global_load_dword v233, v[238:239], off offset:192 sc1
	global_load_dword v234, v[238:239], off offset:512 sc1
	global_load_dword v235, v[238:239], off offset:576 sc1
	global_load_dword v236, v[238:239], off offset:640 sc1
	global_load_dword v237, v[238:239], off offset:704 sc1
	v_mul_f32_e32 v124, v116, v124
	v_mul_f32_e32 v125, v117, v125
	v_mul_f32_e32 v126, v118, v126
	v_mul_f32_e32 v127, v119, v127
	v_mul_f32_e32 v158, v112, v120
	v_mul_f32_e32 v159, v113, v121
	v_mul_f32_e32 v160, v114, v122
	v_mul_f32_e32 v161, v115, v123
	v_mul_f32_e32 v107, v111, v107
	v_mov_b64_e32 v[120:121], s[56:57]
	v_mad_i64_i32 v[122:123], s[28:29], v144, s50, v[120:121]
	v_lshl_add_u64 v[122:123], v[122:123], 0, v[104:105]
	v_mul_f32_e32 v96, v100, v96
	v_mul_f32_e32 v98, v102, v98
	v_mul_f32_e32 v88, v92, v88
	v_mul_f32_e32 v89, v93, v89
	v_mul_f32_e32 v90, v94, v90
	v_mul_f32_e32 v91, v95, v91
	v_mul_f32_e32 v80, v84, v80
	v_mul_f32_e32 v82, v86, v82
	v_mul_f32_e32 v72, v76, v72
	v_mul_f32_e32 v73, v77, v73
	v_mul_f32_e32 v74, v78, v74
	v_mul_f32_e32 v75, v79, v75
	v_mul_f32_e32 v64, v68, v64
	v_mul_f32_e32 v66, v70, v66
	v_mul_f32_e32 v56, v60, v56
	v_mul_f32_e32 v57, v61, v57
	v_mul_f32_e32 v58, v62, v58
	v_mul_f32_e32 v59, v63, v59
	v_mul_f32_e32 v48, v52, v48
	v_mul_f32_e32 v50, v54, v50
	v_mul_f32_e32 v40, v44, v40
	v_mul_f32_e32 v41, v45, v41
	v_mul_f32_e32 v42, v46, v42
	v_mul_f32_e32 v43, v47, v43
	v_mul_f32_e32 v32, v36, v32
	v_mul_f32_e32 v34, v38, v34
	v_mul_f32_e32 v24, v28, v24
	v_mul_f32_e32 v25, v29, v25
	v_mul_f32_e32 v26, v30, v26
	v_mul_f32_e32 v27, v31, v27
	v_mul_f32_e32 v16, v20, v16
	v_mul_f32_e32 v18, v22, v18
	v_mul_f32_e32 v8, v12, v8
	v_mul_f32_e32 v9, v13, v9
	v_mul_f32_e32 v10, v14, v10
	v_mul_f32_e32 v11, v15, v11
	v_mul_f32_e32 v0, v4, v0
	v_mul_f32_e32 v2, v6, v2
	s_andn2_b64 vcc, exec, s[6:7]
	s_mov_b64 s[6:7], -1
	v_fmamk_f32 v145, v145, 0x3a800000, v152
	v_fmamk_f32 v153, v153, 0x3a800000, v152
	v_rsq_f32_e32 v168, v145
	v_rsq_f32_e32 v169, v153
	v_mul_f32_e32 v154, 0xbfb8aa3b, v168
	v_mul_f32_e32 v155, 0xbfb8aa3b, v169
	v_mul_f32_e32 v116, v116, v154
	v_mul_f32_e32 v117, v117, v154
	v_mul_f32_e32 v118, v118, v154
	v_mul_f32_e32 v119, v119, v154
	v_mul_f32_e32 v112, v112, v154
	v_mul_f32_e32 v113, v113, v154
	v_mul_f32_e32 v114, v114, v154
	v_mul_f32_e32 v115, v115, v154
	v_mul_f32_e32 v108, v108, v155
	v_mul_f32_e32 v109, v109, v155
	v_mul_f32_e32 v110, v110, v155
	v_exp_f32_e32 v116, v116
	v_exp_f32_e32 v117, v117
	v_exp_f32_e32 v118, v118
	v_exp_f32_e32 v119, v119
	v_exp_f32_e32 v112, v112
	v_exp_f32_e32 v113, v113
	v_exp_f32_e32 v114, v114
	v_exp_f32_e32 v115, v115
	v_exp_f32_e32 v108, v108
	v_exp_f32_e32 v109, v109
	v_exp_f32_e32 v110, v110
	v_mul_f32_e32 v111, v111, v155
	v_exp_f32_e32 v111, v111
	v_fma_f32 v116, v145, v116, v145
	v_fma_f32 v117, v145, v117, v145
	v_fma_f32 v118, v145, v118, v145
	v_fma_f32 v119, v145, v119, v145
	v_fma_f32 v112, v145, v112, v145
	v_fma_f32 v113, v145, v113, v145
	v_fma_f32 v114, v145, v114, v145
	v_fmac_f32_e32 v145, v145, v115
	v_fma_f32 v108, v153, v108, v153
	v_fma_f32 v109, v153, v109, v153
	v_mul_f32_e32 v154, v100, v155
	v_fma_f32 v110, v153, v110, v153
	v_rcp_f32_e32 v115, v116
	v_rcp_f32_e32 v116, v117
	v_rcp_f32_e32 v117, v118
	v_rcp_f32_e32 v118, v119
	v_rcp_f32_e32 v119, v145
	v_rcp_f32_e32 v108, v108
	v_rcp_f32_e32 v109, v109
	v_exp_f32_e32 v154, v154
	v_rcp_f32_e32 v112, v112
	v_rcp_f32_e32 v113, v113
	v_rcp_f32_e32 v114, v114
	v_rcp_f32_e32 v110, v110
	v_fma_f32 v111, v153, v111, v153
	v_rcp_f32_e32 v145, v111
	v_mul_f32_e32 v111, v124, v115
	v_mul_f32_e32 v115, v125, v116
	v_mul_f32_e32 v116, v126, v117
	v_mul_f32_e32 v117, v127, v118
	v_mul_f32_e32 v118, v161, v119
	v_mul_f32_e32 v119, v162, v108
	v_mul_f32_e32 v124, v163, v109
	v_cvt_pk_bf16_f32 v108, v111, v115
	v_cvt_pk_bf16_f32 v109, v116, v117
	v_mul_f32_e32 v112, v158, v112
	v_mul_f32_e32 v113, v159, v113
	v_mul_f32_e32 v114, v160, v114
	v_mul_f32_e32 v125, v164, v110
	v_cvt_pk_bf16_f32 v110, v112, v113
	v_cvt_pk_bf16_f32 v111, v114, v118
	global_store_dwordx4 v[122:123], v[108:111], off
	v_mul_f32_e32 v107, v107, v145
	s_nop 0
	v_fma_f32 v108, v153, v154, v153
	v_mul_f32_e32 v109, v101, v155
	v_rcp_f32_e32 v108, v108
	v_exp_f32_e32 v109, v109
	v_mul_f32_e32 v100, v96, v108
	v_mul_f32_e32 v96, v101, v97
	v_fma_f32 v97, v153, v109, v153
	v_mul_f32_e32 v101, v102, v155
	v_rcp_f32_e32 v97, v97
	v_exp_f32_e32 v101, v101
	v_mul_f32_e32 v108, v103, v155
	v_exp_f32_e32 v108, v108
	v_mul_f32_e32 v109, v96, v97
	v_fma_f32 v96, v153, v101, v153
	v_rcp_f32_e32 v96, v96
	v_fmac_f32_e32 v153, v153, v108
	v_rcp_f32_e32 v97, v153
	v_or_b32_e32 v102, 16, v144
	v_mul_f32_e32 v101, v98, v96
	v_mul_f32_e32 v96, v103, v99
	v_fmamk_f32 v103, v156, 0x3a800000, v152
	v_mul_f32_e32 v99, v96, v97
	v_cvt_pk_bf16_f32 v96, v119, v124
	v_cvt_pk_bf16_f32 v97, v125, v107
	v_rsq_f32_e32 v107, v103
	v_cvt_pk_bf16_f32 v98, v100, v109
	v_cvt_pk_bf16_f32 v99, v101, v99
	v_mad_i64_i32 v[100:101], s[28:29], v102, s50, v[120:121]
	v_mul_f32_e32 v102, 0xbfb8aa3b, v107
	v_mul_f32_e32 v107, v92, v102
	v_mul_f32_e32 v108, v93, v102
	v_mul_f32_e32 v92, v94, v102
	v_mul_f32_e32 v93, v95, v102
	v_exp_f32_e32 v92, v92
	v_exp_f32_e32 v93, v93
	v_mul_f32_e32 v94, v84, v102
	v_exp_f32_e32 v94, v94
	v_fma_f32 v92, v103, v92, v103
	v_fma_f32 v93, v103, v93, v103
	v_rcp_f32_e32 v92, v92
	v_rcp_f32_e32 v93, v93
	v_exp_f32_e32 v107, v107
	v_exp_f32_e32 v108, v108
	v_mul_f32_e32 v90, v90, v92
	v_mul_f32_e32 v91, v91, v93
	v_fma_f32 v92, v103, v94, v103
	v_mul_f32_e32 v93, v85, v102
	v_rcp_f32_e32 v92, v92
	v_exp_f32_e32 v93, v93
	v_lshl_add_u64 v[100:101], v[100:101], 0, v[104:105]
	global_store_dwordx4 v[100:101], v[96:99], off
	v_mul_f32_e32 v84, v80, v92
	v_mul_f32_e32 v80, v85, v81
	v_fma_f32 v81, v103, v93, v103
	v_mul_f32_e32 v85, v86, v102
	v_rcp_f32_e32 v81, v81
	v_exp_f32_e32 v85, v85
	v_mul_f32_e32 v92, v87, v102
	v_exp_f32_e32 v92, v92
	v_fma_f32 v96, v103, v107, v103
	v_mul_f32_e32 v93, v80, v81
	v_fma_f32 v80, v103, v85, v103
	v_rcp_f32_e32 v96, v96
	v_fma_f32 v97, v103, v108, v103
	v_rcp_f32_e32 v80, v80
	v_fmac_f32_e32 v103, v103, v92
	v_rcp_f32_e32 v97, v97
	v_rcp_f32_e32 v81, v103
	v_mul_f32_e32 v88, v88, v96
	v_mul_f32_e32 v85, v82, v80
	v_mul_f32_e32 v80, v87, v83
	v_fmamk_f32 v87, v157, 0x3a800000, v152
	v_mul_f32_e32 v89, v89, v97
	v_mul_f32_e32 v83, v80, v81
	v_cvt_pk_bf16_f32 v80, v88, v89
	v_rsq_f32_e32 v88, v87
	v_or_b32_e32 v86, 32, v144
	v_cvt_pk_bf16_f32 v81, v90, v91
	v_cvt_pk_bf16_f32 v82, v84, v93
	v_cvt_pk_bf16_f32 v83, v85, v83
	v_mad_i64_i32 v[84:85], s[28:29], v86, s50, v[120:121]
	v_mul_f32_e32 v86, 0xbfb8aa3b, v88
	v_mul_f32_e32 v88, v76, v86
	v_mul_f32_e32 v89, v77, v86
	v_mul_f32_e32 v76, v78, v86
	v_mul_f32_e32 v77, v79, v86
	v_exp_f32_e32 v76, v76
	v_exp_f32_e32 v77, v77
	v_mul_f32_e32 v78, v68, v86
	v_exp_f32_e32 v78, v78
	v_fma_f32 v76, v87, v76, v87
	v_fma_f32 v77, v87, v77, v87
	v_rcp_f32_e32 v76, v76
	v_rcp_f32_e32 v77, v77
	v_exp_f32_e32 v88, v88
	v_exp_f32_e32 v89, v89
	v_mul_f32_e32 v74, v74, v76
	v_mul_f32_e32 v75, v75, v77
	v_fma_f32 v76, v87, v78, v87
	v_mul_f32_e32 v77, v69, v86
	v_rcp_f32_e32 v76, v76
	v_exp_f32_e32 v77, v77
	v_lshl_add_u64 v[84:85], v[84:85], 0, v[104:105]
	global_store_dwordx4 v[84:85], v[80:83], off
	v_mul_f32_e32 v68, v64, v76
	v_mul_f32_e32 v64, v69, v65
	v_fma_f32 v65, v87, v77, v87
	v_mul_f32_e32 v69, v70, v86
	v_rcp_f32_e32 v65, v65
	v_exp_f32_e32 v69, v69
	v_mul_f32_e32 v76, v71, v86
	v_exp_f32_e32 v76, v76
	v_fma_f32 v80, v87, v88, v87
	v_mul_f32_e32 v77, v64, v65
	v_fma_f32 v64, v87, v69, v87
	v_rcp_f32_e32 v80, v80
	v_fma_f32 v81, v87, v89, v87
	v_rcp_f32_e32 v64, v64
	v_fmac_f32_e32 v87, v87, v76
	v_rcp_f32_e32 v81, v81
	v_rcp_f32_e32 v65, v87
	v_mul_f32_e32 v72, v72, v80
	v_mul_f32_e32 v69, v66, v64
	v_mul_f32_e32 v64, v71, v67
	v_fmamk_f32 v71, v165, 0x3a800000, v152
	v_mul_f32_e32 v73, v73, v81
	v_mul_f32_e32 v67, v64, v65
	v_cvt_pk_bf16_f32 v64, v72, v73
	v_rsq_f32_e32 v72, v71
	v_or_b32_e32 v70, 48, v144
	v_cvt_pk_bf16_f32 v65, v74, v75
	v_cvt_pk_bf16_f32 v66, v68, v77
	v_cvt_pk_bf16_f32 v67, v69, v67
	v_mad_i64_i32 v[68:69], s[28:29], v70, s50, v[120:121]
	v_lshl_add_u64 v[68:69], v[68:69], 0, v[104:105]
	global_store_dwordx4 v[68:69], v[64:67], off
	s_nop 1
	v_mul_f32_e32 v64, 0xbfb8aa3b, v72
	v_mul_f32_e32 v65, v60, v64
	v_mul_f32_e32 v66, v61, v64
	v_mul_f32_e32 v60, v62, v64
	v_mul_f32_e32 v61, v63, v64
	v_exp_f32_e32 v60, v60
	v_exp_f32_e32 v61, v61
	v_mul_f32_e32 v62, v52, v64
	v_exp_f32_e32 v62, v62
	v_fma_f32 v60, v71, v60, v71
	v_fma_f32 v61, v71, v61, v71
	v_rcp_f32_e32 v60, v60
	v_rcp_f32_e32 v61, v61
	v_exp_f32_e32 v65, v65
	v_exp_f32_e32 v66, v66
	v_mul_f32_e32 v58, v58, v60
	v_mul_f32_e32 v59, v59, v61
	v_fma_f32 v60, v71, v62, v71
	v_mul_f32_e32 v61, v53, v64
	v_rcp_f32_e32 v60, v60
	v_exp_f32_e32 v61, v61
	v_fma_f32 v65, v71, v65, v71
	v_fma_f32 v66, v71, v66, v71
	v_mul_f32_e32 v52, v48, v60
	v_mul_f32_e32 v48, v53, v49
	v_fma_f32 v49, v71, v61, v71
	v_mul_f32_e32 v53, v54, v64
	v_rcp_f32_e32 v49, v49
	v_exp_f32_e32 v53, v53
	v_mul_f32_e32 v60, v55, v64
	v_exp_f32_e32 v60, v60
	v_mul_f32_e32 v61, v48, v49
	v_fma_f32 v48, v71, v53, v71
	v_rcp_f32_e32 v48, v48
	v_fmamk_f32 v54, v166, 0x3a800000, v152
	v_rcp_f32_e32 v65, v65
	v_rcp_f32_e32 v66, v66
	v_fmac_f32_e32 v71, v71, v60
	v_mul_f32_e32 v53, v50, v48
	v_mul_f32_e32 v48, v55, v51
	v_rsq_f32_e32 v55, v54
	v_rcp_f32_e32 v49, v71
	v_mul_f32_e32 v56, v56, v65
	v_mul_f32_e32 v57, v57, v66
	v_mul_f32_e32 v55, 0xbfb8aa3b, v55
	v_mul_f32_e32 v51, v48, v49
	v_cvt_pk_bf16_f32 v48, v56, v57
	v_mul_f32_e32 v56, v44, v55
	v_mul_f32_e32 v57, v45, v55
	v_mul_f32_e32 v44, v46, v55
	v_mul_f32_e32 v45, v47, v55
	v_exp_f32_e32 v44, v44
	v_exp_f32_e32 v45, v45
	v_mul_f32_e32 v46, v36, v55
	v_exp_f32_e32 v46, v46
	v_fma_f32 v44, v54, v44, v54
	v_fma_f32 v45, v54, v45, v54
	v_rcp_f32_e32 v44, v44
	v_rcp_f32_e32 v45, v45
	v_exp_f32_e32 v56, v56
	v_add_u32_e32 v67, 0x80, v144
	v_mul_f32_e32 v42, v42, v44
	v_mul_f32_e32 v43, v43, v45
	v_fma_f32 v44, v54, v46, v54
	v_mul_f32_e32 v45, v37, v55
	v_rcp_f32_e32 v44, v44
	v_exp_f32_e32 v45, v45
	v_exp_f32_e32 v57, v57
	v_cvt_pk_bf16_f32 v49, v58, v59
	v_mul_f32_e32 v36, v32, v44
	v_mul_f32_e32 v32, v37, v33
	v_fma_f32 v33, v54, v45, v54
	v_mul_f32_e32 v37, v38, v55
	v_rcp_f32_e32 v33, v33
	v_exp_f32_e32 v37, v37
	v_mul_f32_e32 v44, v39, v55
	v_exp_f32_e32 v44, v44
	v_cvt_pk_bf16_f32 v50, v52, v61
	v_cvt_pk_bf16_f32 v51, v53, v51
	v_mad_i64_i32 v[52:53], s[28:29], v67, s50, v[120:121]
	v_lshl_add_u64 v[52:53], v[52:53], 0, v[104:105]
	global_store_dwordx4 v[52:53], v[48:51], off
	v_mul_f32_e32 v45, v32, v33
	v_fma_f32 v32, v54, v37, v54
	v_fma_f32 v48, v54, v56, v54
	v_rcp_f32_e32 v48, v48
	v_fma_f32 v49, v54, v57, v54
	v_rcp_f32_e32 v32, v32
	v_fmac_f32_e32 v54, v54, v44
	v_rcp_f32_e32 v49, v49
	v_rcp_f32_e32 v33, v54
	v_mul_f32_e32 v40, v40, v48
	v_mul_f32_e32 v37, v34, v32
	v_mul_f32_e32 v32, v39, v35
	v_fmamk_f32 v39, v167, 0x3a800000, v152
	v_mul_f32_e32 v41, v41, v49
	v_mul_f32_e32 v35, v32, v33
	v_cvt_pk_bf16_f32 v32, v40, v41
	v_rsq_f32_e32 v40, v39
	v_add_u32_e32 v38, 0x90, v144
	v_cvt_pk_bf16_f32 v33, v42, v43
	v_cvt_pk_bf16_f32 v34, v36, v45
	v_cvt_pk_bf16_f32 v35, v37, v35
	v_mad_i64_i32 v[36:37], s[28:29], v38, s50, v[120:121]
	v_mul_f32_e32 v38, 0xbfb8aa3b, v40
	v_mul_f32_e32 v40, v28, v38
	v_mul_f32_e32 v41, v29, v38
	v_mul_f32_e32 v28, v30, v38
	v_mul_f32_e32 v29, v31, v38
	v_exp_f32_e32 v28, v28
	v_exp_f32_e32 v29, v29
	v_mul_f32_e32 v30, v20, v38
	v_exp_f32_e32 v30, v30
	v_fma_f32 v28, v39, v28, v39
	v_fma_f32 v29, v39, v29, v39
	v_rcp_f32_e32 v28, v28
	v_rcp_f32_e32 v29, v29
	v_exp_f32_e32 v40, v40
	v_exp_f32_e32 v41, v41
	v_mul_f32_e32 v26, v26, v28
	v_mul_f32_e32 v27, v27, v29
	v_fma_f32 v28, v39, v30, v39
	v_mul_f32_e32 v29, v21, v38
	v_rcp_f32_e32 v28, v28
	v_exp_f32_e32 v29, v29
	v_lshl_add_u64 v[36:37], v[36:37], 0, v[104:105]
	global_store_dwordx4 v[36:37], v[32:35], off
	v_mul_f32_e32 v20, v16, v28
	v_mul_f32_e32 v16, v21, v17
	v_fma_f32 v17, v39, v29, v39
	v_mul_f32_e32 v21, v22, v38
	v_rcp_f32_e32 v17, v17
	v_exp_f32_e32 v21, v21
	v_mul_f32_e32 v28, v23, v38
	v_exp_f32_e32 v28, v28
	v_fma_f32 v32, v39, v40, v39
	v_mul_f32_e32 v29, v16, v17
	v_fma_f32 v16, v39, v21, v39
	v_rcp_f32_e32 v32, v32
	v_fma_f32 v33, v39, v41, v39
	v_rcp_f32_e32 v16, v16
	v_fmac_f32_e32 v39, v39, v28
	v_rcp_f32_e32 v33, v33
	v_rcp_f32_e32 v17, v39
	v_mul_f32_e32 v24, v24, v32
	v_mul_f32_e32 v21, v18, v16
	v_mul_f32_e32 v16, v23, v19
	v_fmamk_f32 v23, v106, 0x3a800000, v152
	v_mul_f32_e32 v25, v25, v33
	v_mul_f32_e32 v19, v16, v17
	v_cvt_pk_bf16_f32 v16, v24, v25
	v_rsq_f32_e32 v24, v23
	v_add_u32_e32 v22, 0xa0, v144
	v_cvt_pk_bf16_f32 v17, v26, v27
	v_cvt_pk_bf16_f32 v18, v20, v29
	v_cvt_pk_bf16_f32 v19, v21, v19
	v_mad_i64_i32 v[20:21], s[28:29], v22, s50, v[120:121]
	v_mul_f32_e32 v22, 0xbfb8aa3b, v24
	v_mul_f32_e32 v24, v12, v22
	v_mul_f32_e32 v25, v13, v22
	v_mul_f32_e32 v12, v14, v22
	v_mul_f32_e32 v13, v15, v22
	v_exp_f32_e32 v12, v12
	v_exp_f32_e32 v13, v13
	v_mul_f32_e32 v14, v4, v22
	v_exp_f32_e32 v14, v14
	v_fma_f32 v12, v23, v12, v23
	v_fma_f32 v13, v23, v13, v23
	v_rcp_f32_e32 v12, v12
	v_rcp_f32_e32 v13, v13
	v_exp_f32_e32 v24, v24
	v_exp_f32_e32 v25, v25
	v_mul_f32_e32 v10, v10, v12
	v_mul_f32_e32 v11, v11, v13
	v_fma_f32 v12, v23, v14, v23
	v_mul_f32_e32 v13, v5, v22
	v_rcp_f32_e32 v12, v12
	v_exp_f32_e32 v13, v13
	v_lshl_add_u64 v[20:21], v[20:21], 0, v[104:105]
	global_store_dwordx4 v[20:21], v[16:19], off
	v_mul_f32_e32 v4, v0, v12
	v_mul_f32_e32 v0, v5, v1
	v_fma_f32 v1, v23, v13, v23
	v_mul_f32_e32 v5, v6, v22
	v_rcp_f32_e32 v1, v1
	v_exp_f32_e32 v5, v5
	v_mul_f32_e32 v12, v7, v22
	v_exp_f32_e32 v12, v12
	v_mul_f32_e32 v13, v0, v1
	v_fma_f32 v0, v23, v5, v23
	v_fma_f32 v16, v23, v24, v23
	v_fma_f32 v17, v23, v25, v23
	v_rcp_f32_e32 v0, v0
	v_fmac_f32_e32 v23, v23, v12
	v_rcp_f32_e32 v1, v23
	v_rcp_f32_e32 v16, v16
	v_rcp_f32_e32 v17, v17
	v_mul_f32_e32 v5, v2, v0
	v_mul_f32_e32 v0, v7, v3
	v_mul_f32_e32 v3, v0, v1
	v_add_u32_e32 v6, 0xb0, v144
	v_mul_f32_e32 v8, v8, v16
	v_mul_f32_e32 v9, v9, v17
	v_cvt_pk_bf16_f32 v0, v8, v9
	v_cvt_pk_bf16_f32 v1, v10, v11
	v_cvt_pk_bf16_f32 v2, v4, v13
	v_cvt_pk_bf16_f32 v3, v5, v3
	v_mad_i64_i32 v[4:5], s[28:29], v6, s50, v[120:121]
	v_lshl_add_u64 v[4:5], v[4:5], 0, v[104:105]
	global_store_dwordx4 v[4:5], v[0:3], off
	s_cbranch_vccnz .LBB0_551
	s_andn2_b64 vcc, exec, s[10:11]
	s_cbranch_vccnz .LBB0_550
	s_barrier
	s_branch .LBB0_550

.LBB0_1187:
	s_lshl_b32 s12, s12, 5
	s_and_b32 s17, s12, 0x60
	s_mov_b64 s[12:13], 0x80
	s_add_i32 m0, s25, 0x18000
	v_lshl_add_u64 v[6:7], v[6:7], 0, s[12:13]
	s_lshl_b32 s16, s7, 13
	s_lshl_b32 s18, s17, 7
	s_waitcnt vmcnt(2)
	s_barrier
	global_load_lds_dwordx4 v[6:7], off
	v_lshl_add_u64 v[4:5], v[4:5], 0, s[12:13]
	s_add_i32 m0, s25, 0x1a000
	s_add_i32 s41, s25, 0x8000
	s_add_i32 s42, s25, 0xa000
	global_load_lds_dwordx4 v[4:5], off
	v_lshl_add_u64 v[0:1], v[0:1], 0, s[12:13]
	s_mov_b32 m0, s41
	s_add_u32 s14, s30, 0x40080
	global_load_lds_dwordx4 v[0:1], off
	v_lshl_add_u64 v[0:1], v[2:3], 0, s[12:13]
	s_mov_b32 m0, s42
	s_addc_u32 s15, s31, 0
	global_load_lds_dwordx4 v[0:1], off
	s_add_i32 m0, s25, 0x1c000
	v_lshl_add_u64 v[0:1], s[14:15], 0, v[132:133]
	global_load_lds_dwordx4 v[0:1], off
	v_lshl_add_u64 v[0:1], s[14:15], 0, v[128:129]
	s_add_i32 m0, s25, 0x1e000
	s_cmpk_lt_u32 s6, 0x100
	global_load_lds_dwordx4 v[0:1], off
	v_lshrrev_b32_e32 v1, 1, v9
	v_and_b32_e32 v1, 24, v1
	v_and_b32_e32 v0, 15, v9
	v_lshlrev_b32_e32 v2, 1, v1
	v_lshl_or_b32 v146, s7, 6, v0
	v_lshl_or_b32 v0, v0, 6, v2
	v_lshlrev_b32_e32 v2, 2, v9
	v_and_b32_e32 v2, 32, v2
	v_bitop3_b32 v3, v0, s16, v2 bitop3:0xde
	v_bitop3_b32 v147, v0, s18, v2 bitop3:0xde
	v_lshlrev_b32_e32 v0, 14, v13
	v_and_b32_e32 v0, 0xffff8000, v0
	v_or_b32_e32 v148, s17, v1
	v_lshl_add_u32 v0, v12, 11, v0
	v_and_b32_e32 v1, 1, v13
	v_lshl_or_b32 v0, v1, 6, v0
	v_lshl_add_u32 v136, v14, 1, v0
	v_lshlrev_b32_e32 v0, 14, v8
	v_and_b32_e32 v0, 0xffff8000, v0
	s_waitcnt vmcnt(6)
	v_lshl_add_u32 v0, v10, 11, v0
	v_and_b32_e32 v1, 1, v8
	s_cselect_b64 s[14:15], -1, 0
	v_lshl_or_b32 v0, v1, 6, v0
	s_add_i32 s47, 0, 0x10000
	s_add_i32 s48, 0, 0x14000
	s_ashr_i32 s43, s52, 31
	s_mov_b32 s46, s52
	v_mov_b32_e32 v137, v133
	v_lshl_add_u32 v138, v11, 1, v0
	v_mov_b32_e32 v139, v133
	v_mov_b64_e32 v[140:141], 0xb00
	v_mov_b64_e32 v[142:143], 0xaff
	v_add_u32_e32 v149, s47, v147
	v_add_u32_e32 v150, s48, v147
	v_add_u32_e32 v151, 0, v3
	v_mov_b32_e32 v152, 0x358637bd
	s_movk_i32 s49, 0x1600
	s_barrier
	v_lshl_add_u32 v238, s26, 8, v146
	v_ashrrev_i32_e32 v239, 31, v238
	v_lshl_add_u64 v[238:239], v[238:239], 2, s[8:9]
	global_load_dword v230, v[238:239], off sc1
	global_load_dword v231, v[238:239], off offset:64 sc1
	global_load_dword v232, v[238:239], off offset:128 sc1
	global_load_dword v233, v[238:239], off offset:192 sc1
	global_load_dword v234, v[238:239], off offset:512 sc1
	global_load_dword v235, v[238:239], off offset:576 sc1
	global_load_dword v236, v[238:239], off offset:640 sc1
	global_load_dword v237, v[238:239], off offset:704 sc1
	s_branch .LBB0_1190

.LBB0_1196:
	v_lshl_add_u32 v144, s26, 8, v146
	v_mov_b32_e32 v145, v230
	v_mov_b32_e32 v153, v231
	v_lshl_or_b32 v156, s24, 7, v148
	v_ashrrev_i32_e32 v157, 31, v156
	v_mul_f32_e32 v162, v108, v104
	v_mul_f32_e32 v163, v109, v105
	v_lshlrev_b64 v[104:105], 1, v[156:157]
	v_mov_b32_e32 v156, v232
	v_mov_b32_e32 v157, v233
	v_mov_b32_e32 v165, v234
	v_mov_b32_e32 v166, v235
	v_mov_b32_e32 v167, v236
	v_mul_f32_e32 v164, v110, v106
	v_mov_b32_e32 v106, v237
	s_and_b64 s[98:99], s[6:7], exec
	s_cselect_b32 s98, s18, s26
	v_lshl_add_u32 v238, s98, 8, v146
	v_ashrrev_i32_e32 v239, 31, v238
	v_lshl_add_u64 v[238:239], v[238:239], 2, s[8:9]
	global_load_dword v230, v[238:239], off sc1
	global_load_dword v231, v[238:239], off offset:64 sc1
	global_load_dword v232, v[238:239], off offset:128 sc1
	global_load_dword v233, v[238:239], off offset:192 sc1
	global_load_dword v234, v[238:239], off offset:512 sc1
	global_load_dword v235, v[238:239], off offset:576 sc1
	global_load_dword v236, v[238:239], off offset:640 sc1
	global_load_dword v237, v[238:239], off offset:704 sc1
	v_mul_f32_e32 v124, v116, v124
	v_mul_f32_e32 v125, v117, v125
	v_mul_f32_e32 v126, v118, v126
	v_mul_f32_e32 v127, v119, v127
	v_mul_f32_e32 v158, v112, v120
	v_mul_f32_e32 v159, v113, v121
	v_mul_f32_e32 v160, v114, v122
	v_mul_f32_e32 v161, v115, v123
	v_mul_f32_e32 v107, v111, v107
	v_mov_b64_e32 v[120:121], s[56:57]
	v_mad_i64_i32 v[122:123], s[28:29], v144, s49, v[120:121]
	v_lshl_add_u64 v[122:123], v[122:123], 0, v[104:105]
	v_mul_f32_e32 v96, v100, v96
	v_mul_f32_e32 v98, v102, v98
	v_mul_f32_e32 v88, v92, v88
	v_mul_f32_e32 v89, v93, v89
	v_mul_f32_e32 v90, v94, v90
	v_mul_f32_e32 v91, v95, v91
	v_mul_f32_e32 v80, v84, v80
	v_mul_f32_e32 v82, v86, v82
	v_mul_f32_e32 v72, v76, v72
	v_mul_f32_e32 v73, v77, v73
	v_mul_f32_e32 v74, v78, v74
	v_mul_f32_e32 v75, v79, v75
	v_mul_f32_e32 v64, v68, v64
	v_mul_f32_e32 v66, v70, v66
	v_mul_f32_e32 v56, v60, v56
	v_mul_f32_e32 v57, v61, v57
	v_mul_f32_e32 v58, v62, v58
	v_mul_f32_e32 v59, v63, v59
	v_mul_f32_e32 v48, v52, v48
	v_mul_f32_e32 v50, v54, v50
	v_mul_f32_e32 v40, v44, v40
	v_mul_f32_e32 v41, v45, v41
	v_mul_f32_e32 v42, v46, v42
	v_mul_f32_e32 v43, v47, v43
	v_mul_f32_e32 v32, v36, v32
	v_mul_f32_e32 v34, v38, v34
	v_mul_f32_e32 v24, v28, v24
	v_mul_f32_e32 v25, v29, v25
	v_mul_f32_e32 v26, v30, v26
	v_mul_f32_e32 v27, v31, v27
	v_mul_f32_e32 v16, v20, v16
	v_mul_f32_e32 v18, v22, v18
	v_mul_f32_e32 v8, v12, v8
	v_mul_f32_e32 v9, v13, v9
	v_mul_f32_e32 v10, v14, v10
	v_mul_f32_e32 v11, v15, v11
	v_mul_f32_e32 v0, v4, v0
	v_mul_f32_e32 v2, v6, v2
	s_andn2_b64 vcc, exec, s[6:7]
	s_mov_b64 s[6:7], -1
	v_fmamk_f32 v145, v145, 0x3a800000, v152
	v_fmamk_f32 v153, v153, 0x3a800000, v152
	v_rsq_f32_e32 v168, v145
	v_rsq_f32_e32 v169, v153
	v_mul_f32_e32 v154, 0xbfb8aa3b, v168
	v_mul_f32_e32 v155, 0xbfb8aa3b, v169
	v_mul_f32_e32 v116, v116, v154
	v_mul_f32_e32 v117, v117, v154
	v_mul_f32_e32 v118, v118, v154
	v_mul_f32_e32 v119, v119, v154
	v_mul_f32_e32 v112, v112, v154
	v_mul_f32_e32 v113, v113, v154
	v_mul_f32_e32 v114, v114, v154
	v_mul_f32_e32 v115, v115, v154
	v_mul_f32_e32 v108, v108, v155
	v_mul_f32_e32 v109, v109, v155
	v_mul_f32_e32 v110, v110, v155
	v_exp_f32_e32 v116, v116
	v_exp_f32_e32 v117, v117
	v_exp_f32_e32 v118, v118
	v_exp_f32_e32 v119, v119
	v_exp_f32_e32 v112, v112
	v_exp_f32_e32 v113, v113
	v_exp_f32_e32 v114, v114
	v_exp_f32_e32 v115, v115
	v_exp_f32_e32 v108, v108
	v_exp_f32_e32 v109, v109
	v_exp_f32_e32 v110, v110
	v_mul_f32_e32 v111, v111, v155
	v_exp_f32_e32 v111, v111
	v_fma_f32 v116, v145, v116, v145
	v_fma_f32 v117, v145, v117, v145
	v_fma_f32 v118, v145, v118, v145
	v_fma_f32 v119, v145, v119, v145
	v_fma_f32 v112, v145, v112, v145
	v_fma_f32 v113, v145, v113, v145
	v_fma_f32 v114, v145, v114, v145
	v_fmac_f32_e32 v145, v145, v115
	v_fma_f32 v108, v153, v108, v153
	v_fma_f32 v109, v153, v109, v153
	v_mul_f32_e32 v154, v100, v155
	v_fma_f32 v110, v153, v110, v153
	v_rcp_f32_e32 v115, v116
	v_rcp_f32_e32 v116, v117
	v_rcp_f32_e32 v117, v118
	v_rcp_f32_e32 v118, v119
	v_rcp_f32_e32 v119, v145
	v_rcp_f32_e32 v108, v108
	v_rcp_f32_e32 v109, v109
	v_exp_f32_e32 v154, v154
	v_rcp_f32_e32 v112, v112
	v_rcp_f32_e32 v113, v113
	v_rcp_f32_e32 v114, v114
	v_rcp_f32_e32 v110, v110
	v_fma_f32 v111, v153, v111, v153
	v_rcp_f32_e32 v145, v111
	v_mul_f32_e32 v111, v124, v115
	v_mul_f32_e32 v115, v125, v116
	v_mul_f32_e32 v116, v126, v117
	v_mul_f32_e32 v117, v127, v118
	v_mul_f32_e32 v118, v161, v119
	v_mul_f32_e32 v119, v162, v108
	v_mul_f32_e32 v124, v163, v109
	v_cvt_pk_bf16_f32 v108, v111, v115
	v_cvt_pk_bf16_f32 v109, v116, v117
	v_mul_f32_e32 v112, v158, v112
	v_mul_f32_e32 v113, v159, v113
	v_mul_f32_e32 v114, v160, v114
	v_mul_f32_e32 v125, v164, v110
	v_cvt_pk_bf16_f32 v110, v112, v113
	v_cvt_pk_bf16_f32 v111, v114, v118
	global_store_dwordx4 v[122:123], v[108:111], off
	v_mul_f32_e32 v107, v107, v145
	s_nop 0
	v_fma_f32 v108, v153, v154, v153
	v_mul_f32_e32 v109, v101, v155
	v_rcp_f32_e32 v108, v108
	v_exp_f32_e32 v109, v109
	v_mul_f32_e32 v100, v96, v108
	v_mul_f32_e32 v96, v101, v97
	v_fma_f32 v97, v153, v109, v153
	v_mul_f32_e32 v101, v102, v155
	v_rcp_f32_e32 v97, v97
	v_exp_f32_e32 v101, v101
	v_mul_f32_e32 v108, v103, v155
	v_exp_f32_e32 v108, v108
	v_mul_f32_e32 v109, v96, v97
	v_fma_f32 v96, v153, v101, v153
	v_rcp_f32_e32 v96, v96
	v_fmac_f32_e32 v153, v153, v108
	v_rcp_f32_e32 v97, v153
	v_or_b32_e32 v102, 16, v144
	v_mul_f32_e32 v101, v98, v96
	v_mul_f32_e32 v96, v103, v99
	v_fmamk_f32 v103, v156, 0x3a800000, v152
	v_mul_f32_e32 v99, v96, v97
	v_cvt_pk_bf16_f32 v96, v119, v124
	v_cvt_pk_bf16_f32 v97, v125, v107
	v_rsq_f32_e32 v107, v103
	v_cvt_pk_bf16_f32 v98, v100, v109
	v_cvt_pk_bf16_f32 v99, v101, v99
	v_mad_i64_i32 v[100:101], s[28:29], v102, s49, v[120:121]
	v_mul_f32_e32 v102, 0xbfb8aa3b, v107
	v_mul_f32_e32 v107, v92, v102
	v_mul_f32_e32 v108, v93, v102
	v_mul_f32_e32 v92, v94, v102
	v_mul_f32_e32 v93, v95, v102
	v_exp_f32_e32 v92, v92
	v_exp_f32_e32 v93, v93
	v_mul_f32_e32 v94, v84, v102
	v_exp_f32_e32 v94, v94
	v_fma_f32 v92, v103, v92, v103
	v_fma_f32 v93, v103, v93, v103
	v_rcp_f32_e32 v92, v92
	v_rcp_f32_e32 v93, v93
	v_exp_f32_e32 v107, v107
	v_exp_f32_e32 v108, v108
	v_mul_f32_e32 v90, v90, v92
	v_mul_f32_e32 v91, v91, v93
	v_fma_f32 v92, v103, v94, v103
	v_mul_f32_e32 v93, v85, v102
	v_rcp_f32_e32 v92, v92
	v_exp_f32_e32 v93, v93
	v_lshl_add_u64 v[100:101], v[100:101], 0, v[104:105]
	global_store_dwordx4 v[100:101], v[96:99], off
	v_mul_f32_e32 v84, v80, v92
	v_mul_f32_e32 v80, v85, v81
	v_fma_f32 v81, v103, v93, v103
	v_mul_f32_e32 v85, v86, v102
	v_rcp_f32_e32 v81, v81
	v_exp_f32_e32 v85, v85
	v_mul_f32_e32 v92, v87, v102
	v_exp_f32_e32 v92, v92
	v_fma_f32 v96, v103, v107, v103
	v_mul_f32_e32 v93, v80, v81
	v_fma_f32 v80, v103, v85, v103
	v_rcp_f32_e32 v96, v96
	v_fma_f32 v97, v103, v108, v103
	v_rcp_f32_e32 v80, v80
	v_fmac_f32_e32 v103, v103, v92
	v_rcp_f32_e32 v97, v97
	v_rcp_f32_e32 v81, v103
	v_mul_f32_e32 v88, v88, v96
	v_mul_f32_e32 v85, v82, v80
	v_mul_f32_e32 v80, v87, v83
	v_fmamk_f32 v87, v157, 0x3a800000, v152
	v_mul_f32_e32 v89, v89, v97
	v_mul_f32_e32 v83, v80, v81
	v_cvt_pk_bf16_f32 v80, v88, v89
	v_rsq_f32_e32 v88, v87
	v_or_b32_e32 v86, 32, v144
	v_cvt_pk_bf16_f32 v81, v90, v91
	v_cvt_pk_bf16_f32 v82, v84, v93
	v_cvt_pk_bf16_f32 v83, v85, v83
	v_mad_i64_i32 v[84:85], s[28:29], v86, s49, v[120:121]
	v_mul_f32_e32 v86, 0xbfb8aa3b, v88
	v_mul_f32_e32 v88, v76, v86
	v_mul_f32_e32 v89, v77, v86
	v_mul_f32_e32 v76, v78, v86
	v_mul_f32_e32 v77, v79, v86
	v_exp_f32_e32 v76, v76
	v_exp_f32_e32 v77, v77
	v_mul_f32_e32 v78, v68, v86
	v_exp_f32_e32 v78, v78
	v_fma_f32 v76, v87, v76, v87
	v_fma_f32 v77, v87, v77, v87
	v_rcp_f32_e32 v76, v76
	v_rcp_f32_e32 v77, v77
	v_exp_f32_e32 v88, v88
	v_exp_f32_e32 v89, v89
	v_mul_f32_e32 v74, v74, v76
	v_mul_f32_e32 v75, v75, v77
	v_fma_f32 v76, v87, v78, v87
	v_mul_f32_e32 v77, v69, v86
	v_rcp_f32_e32 v76, v76
	v_exp_f32_e32 v77, v77
	v_lshl_add_u64 v[84:85], v[84:85], 0, v[104:105]
	global_store_dwordx4 v[84:85], v[80:83], off
	v_mul_f32_e32 v68, v64, v76
	v_mul_f32_e32 v64, v69, v65
	v_fma_f32 v65, v87, v77, v87
	v_mul_f32_e32 v69, v70, v86
	v_rcp_f32_e32 v65, v65
	v_exp_f32_e32 v69, v69
	v_mul_f32_e32 v76, v71, v86
	v_exp_f32_e32 v76, v76
	v_fma_f32 v80, v87, v88, v87
	v_mul_f32_e32 v77, v64, v65
	v_fma_f32 v64, v87, v69, v87
	v_rcp_f32_e32 v80, v80
	v_fma_f32 v81, v87, v89, v87
	v_rcp_f32_e32 v64, v64
	v_fmac_f32_e32 v87, v87, v76
	v_rcp_f32_e32 v81, v81
	v_rcp_f32_e32 v65, v87
	v_mul_f32_e32 v72, v72, v80
	v_mul_f32_e32 v69, v66, v64
	v_mul_f32_e32 v64, v71, v67
	v_fmamk_f32 v71, v165, 0x3a800000, v152
	v_mul_f32_e32 v73, v73, v81
	v_mul_f32_e32 v67, v64, v65
	v_cvt_pk_bf16_f32 v64, v72, v73
	v_rsq_f32_e32 v72, v71
	v_or_b32_e32 v70, 48, v144
	v_cvt_pk_bf16_f32 v65, v74, v75
	v_cvt_pk_bf16_f32 v66, v68, v77
	v_cvt_pk_bf16_f32 v67, v69, v67
	v_mad_i64_i32 v[68:69], s[28:29], v70, s49, v[120:121]
	v_lshl_add_u64 v[68:69], v[68:69], 0, v[104:105]
	global_store_dwordx4 v[68:69], v[64:67], off
	s_nop 1
	v_mul_f32_e32 v64, 0xbfb8aa3b, v72
	v_mul_f32_e32 v65, v60, v64
	v_mul_f32_e32 v66, v61, v64
	v_mul_f32_e32 v60, v62, v64
	v_mul_f32_e32 v61, v63, v64
	v_exp_f32_e32 v60, v60
	v_exp_f32_e32 v61, v61
	v_mul_f32_e32 v62, v52, v64
	v_exp_f32_e32 v62, v62
	v_fma_f32 v60, v71, v60, v71
	v_fma_f32 v61, v71, v61, v71
	v_rcp_f32_e32 v60, v60
	v_rcp_f32_e32 v61, v61
	v_exp_f32_e32 v65, v65
	v_exp_f32_e32 v66, v66
	v_mul_f32_e32 v58, v58, v60
	v_mul_f32_e32 v59, v59, v61
	v_fma_f32 v60, v71, v62, v71
	v_mul_f32_e32 v61, v53, v64
	v_rcp_f32_e32 v60, v60
	v_exp_f32_e32 v61, v61
	v_fma_f32 v65, v71, v65, v71
	v_fma_f32 v66, v71, v66, v71
	v_mul_f32_e32 v52, v48, v60
	v_mul_f32_e32 v48, v53, v49
	v_fma_f32 v49, v71, v61, v71
	v_mul_f32_e32 v53, v54, v64
	v_rcp_f32_e32 v49, v49
	v_exp_f32_e32 v53, v53
	v_mul_f32_e32 v60, v55, v64
	v_exp_f32_e32 v60, v60
	v_mul_f32_e32 v61, v48, v49
	v_fma_f32 v48, v71, v53, v71
	v_rcp_f32_e32 v48, v48
	v_fmamk_f32 v54, v166, 0x3a800000, v152
	v_rcp_f32_e32 v65, v65
	v_rcp_f32_e32 v66, v66
	v_fmac_f32_e32 v71, v71, v60
	v_mul_f32_e32 v53, v50, v48
	v_mul_f32_e32 v48, v55, v51
	v_rsq_f32_e32 v55, v54
	v_rcp_f32_e32 v49, v71
	v_mul_f32_e32 v56, v56, v65
	v_mul_f32_e32 v57, v57, v66
	v_mul_f32_e32 v55, 0xbfb8aa3b, v55
	v_mul_f32_e32 v51, v48, v49
	v_cvt_pk_bf16_f32 v48, v56, v57
	v_mul_f32_e32 v56, v44, v55
	v_mul_f32_e32 v57, v45, v55
	v_mul_f32_e32 v44, v46, v55
	v_mul_f32_e32 v45, v47, v55
	v_exp_f32_e32 v44, v44
	v_exp_f32_e32 v45, v45
	v_mul_f32_e32 v46, v36, v55
	v_exp_f32_e32 v46, v46
	v_fma_f32 v44, v54, v44, v54
	v_fma_f32 v45, v54, v45, v54
	v_rcp_f32_e32 v44, v44
	v_rcp_f32_e32 v45, v45
	v_exp_f32_e32 v56, v56
	v_add_u32_e32 v67, 0x80, v144
	v_mul_f32_e32 v42, v42, v44
	v_mul_f32_e32 v43, v43, v45
	v_fma_f32 v44, v54, v46, v54
	v_mul_f32_e32 v45, v37, v55
	v_rcp_f32_e32 v44, v44
	v_exp_f32_e32 v45, v45
	v_exp_f32_e32 v57, v57
	v_cvt_pk_bf16_f32 v49, v58, v59
	v_mul_f32_e32 v36, v32, v44
	v_mul_f32_e32 v32, v37, v33
	v_fma_f32 v33, v54, v45, v54
	v_mul_f32_e32 v37, v38, v55
	v_rcp_f32_e32 v33, v33
	v_exp_f32_e32 v37, v37
	v_mul_f32_e32 v44, v39, v55
	v_exp_f32_e32 v44, v44
	v_cvt_pk_bf16_f32 v50, v52, v61
	v_cvt_pk_bf16_f32 v51, v53, v51
	v_mad_i64_i32 v[52:53], s[28:29], v67, s49, v[120:121]
	v_lshl_add_u64 v[52:53], v[52:53], 0, v[104:105]
	global_store_dwordx4 v[52:53], v[48:51], off
	v_mul_f32_e32 v45, v32, v33
	v_fma_f32 v32, v54, v37, v54
	v_fma_f32 v48, v54, v56, v54
	v_rcp_f32_e32 v48, v48
	v_fma_f32 v49, v54, v57, v54
	v_rcp_f32_e32 v32, v32
	v_fmac_f32_e32 v54, v54, v44
	v_rcp_f32_e32 v49, v49
	v_rcp_f32_e32 v33, v54
	v_mul_f32_e32 v40, v40, v48
	v_mul_f32_e32 v37, v34, v32
	v_mul_f32_e32 v32, v39, v35
	v_fmamk_f32 v39, v167, 0x3a800000, v152
	v_mul_f32_e32 v41, v41, v49
	v_mul_f32_e32 v35, v32, v33
	v_cvt_pk_bf16_f32 v32, v40, v41
	v_rsq_f32_e32 v40, v39
	v_add_u32_e32 v38, 0x90, v144
	v_cvt_pk_bf16_f32 v33, v42, v43
	v_cvt_pk_bf16_f32 v34, v36, v45
	v_cvt_pk_bf16_f32 v35, v37, v35
	v_mad_i64_i32 v[36:37], s[28:29], v38, s49, v[120:121]
	v_mul_f32_e32 v38, 0xbfb8aa3b, v40
	v_mul_f32_e32 v40, v28, v38
	v_mul_f32_e32 v41, v29, v38
	v_mul_f32_e32 v28, v30, v38
	v_mul_f32_e32 v29, v31, v38
	v_exp_f32_e32 v28, v28
	v_exp_f32_e32 v29, v29
	v_mul_f32_e32 v30, v20, v38
	v_exp_f32_e32 v30, v30
	v_fma_f32 v28, v39, v28, v39
	v_fma_f32 v29, v39, v29, v39
	v_rcp_f32_e32 v28, v28
	v_rcp_f32_e32 v29, v29
	v_exp_f32_e32 v40, v40
	v_exp_f32_e32 v41, v41
	v_mul_f32_e32 v26, v26, v28
	v_mul_f32_e32 v27, v27, v29
	v_fma_f32 v28, v39, v30, v39
	v_mul_f32_e32 v29, v21, v38
	v_rcp_f32_e32 v28, v28
	v_exp_f32_e32 v29, v29
	v_lshl_add_u64 v[36:37], v[36:37], 0, v[104:105]
	global_store_dwordx4 v[36:37], v[32:35], off
	v_mul_f32_e32 v20, v16, v28
	v_mul_f32_e32 v16, v21, v17
	v_fma_f32 v17, v39, v29, v39
	v_mul_f32_e32 v21, v22, v38
	v_rcp_f32_e32 v17, v17
	v_exp_f32_e32 v21, v21
	v_mul_f32_e32 v28, v23, v38
	v_exp_f32_e32 v28, v28
	v_fma_f32 v32, v39, v40, v39
	v_mul_f32_e32 v29, v16, v17
	v_fma_f32 v16, v39, v21, v39
	v_rcp_f32_e32 v32, v32
	v_fma_f32 v33, v39, v41, v39
	v_rcp_f32_e32 v16, v16
	v_fmac_f32_e32 v39, v39, v28
	v_rcp_f32_e32 v33, v33
	v_rcp_f32_e32 v17, v39
	v_mul_f32_e32 v24, v24, v32
	v_mul_f32_e32 v21, v18, v16
	v_mul_f32_e32 v16, v23, v19
	v_fmamk_f32 v23, v106, 0x3a800000, v152
	v_mul_f32_e32 v25, v25, v33
	v_mul_f32_e32 v19, v16, v17
	v_cvt_pk_bf16_f32 v16, v24, v25
	v_rsq_f32_e32 v24, v23
	v_add_u32_e32 v22, 0xa0, v144
	v_cvt_pk_bf16_f32 v17, v26, v27
	v_cvt_pk_bf16_f32 v18, v20, v29
	v_cvt_pk_bf16_f32 v19, v21, v19
	v_mad_i64_i32 v[20:21], s[28:29], v22, s49, v[120:121]
	v_mul_f32_e32 v22, 0xbfb8aa3b, v24
	v_mul_f32_e32 v24, v12, v22
	v_mul_f32_e32 v25, v13, v22
	v_mul_f32_e32 v12, v14, v22
	v_mul_f32_e32 v13, v15, v22
	v_exp_f32_e32 v12, v12
	v_exp_f32_e32 v13, v13
	v_mul_f32_e32 v14, v4, v22
	v_exp_f32_e32 v14, v14
	v_fma_f32 v12, v23, v12, v23
	v_fma_f32 v13, v23, v13, v23
	v_rcp_f32_e32 v12, v12
	v_rcp_f32_e32 v13, v13
	v_exp_f32_e32 v24, v24
	v_exp_f32_e32 v25, v25
	v_mul_f32_e32 v10, v10, v12
	v_mul_f32_e32 v11, v11, v13
	v_fma_f32 v12, v23, v14, v23
	v_mul_f32_e32 v13, v5, v22
	v_rcp_f32_e32 v12, v12
	v_exp_f32_e32 v13, v13
	v_lshl_add_u64 v[20:21], v[20:21], 0, v[104:105]
	global_store_dwordx4 v[20:21], v[16:19], off
	v_mul_f32_e32 v4, v0, v12
	v_mul_f32_e32 v0, v5, v1
	v_fma_f32 v1, v23, v13, v23
	v_mul_f32_e32 v5, v6, v22
	v_rcp_f32_e32 v1, v1
	v_exp_f32_e32 v5, v5
	v_mul_f32_e32 v12, v7, v22
	v_exp_f32_e32 v12, v12
	v_mul_f32_e32 v13, v0, v1
	v_fma_f32 v0, v23, v5, v23
	v_fma_f32 v16, v23, v24, v23
	v_fma_f32 v17, v23, v25, v23
	v_rcp_f32_e32 v0, v0
	v_fmac_f32_e32 v23, v23, v12
	v_rcp_f32_e32 v1, v23
	v_rcp_f32_e32 v16, v16
	v_rcp_f32_e32 v17, v17
	v_mul_f32_e32 v5, v2, v0
	v_mul_f32_e32 v0, v7, v3
	v_mul_f32_e32 v3, v0, v1
	v_add_u32_e32 v6, 0xb0, v144
	v_mul_f32_e32 v8, v8, v16
	v_mul_f32_e32 v9, v9, v17
	v_cvt_pk_bf16_f32 v0, v8, v9
	v_cvt_pk_bf16_f32 v1, v10, v11
	v_cvt_pk_bf16_f32 v2, v4, v13
	v_cvt_pk_bf16_f32 v3, v5, v3
	v_mad_i64_i32 v[4:5], s[28:29], v6, s49, v[120:121]
	v_lshl_add_u64 v[4:5], v[4:5], 0, v[104:105]
	global_store_dwordx4 v[4:5], v[0:3], off
	s_cbranch_vccnz .LBB0_1189
	s_andn2_b64 vcc, exec, s[10:11]
	s_cbranch_vccnz .LBB0_1188
	s_barrier
	s_branch .LBB0_1188

	.amdhsa_kernel _Z8yoco_fwd6Params
		.amdhsa_group_segment_fixed_size 0
		.amdhsa_private_segment_fixed_size 0
		.amdhsa_kernarg_size 600
		.amdhsa_user_sgpr_count 2
		.amdhsa_user_sgpr_dispatch_ptr 0
		.amdhsa_user_sgpr_queue_ptr 0
		.amdhsa_user_sgpr_kernarg_segment_ptr 1
		.amdhsa_user_sgpr_dispatch_id 0
		.amdhsa_user_sgpr_kernarg_preload_length 0
		.amdhsa_user_sgpr_kernarg_preload_offset 0
		.amdhsa_user_sgpr_private_segment_size 0
		.amdhsa_uses_dynamic_stack 0
		.amdhsa_enable_private_segment 0
		.amdhsa_system_sgpr_workgroup_id_x 1
		.amdhsa_system_sgpr_workgroup_id_y 0
		.amdhsa_system_sgpr_workgroup_id_z 0
		.amdhsa_system_sgpr_workgroup_info 0
		.amdhsa_system_vgpr_workitem_id 2
		.amdhsa_next_free_vgpr 256
		.amdhsa_next_free_sgpr 102
		.amdhsa_accum_offset 256
		.amdhsa_reserve_vcc 1
		.amdhsa_float_round_mode_32 0
		.amdhsa_float_round_mode_16_64 0
		.amdhsa_float_denorm_mode_32 3
		.amdhsa_float_denorm_mode_16_64 3
		.amdhsa_dx10_clamp 1
		.amdhsa_ieee_mode 1
		.amdhsa_fp16_overflow 0
		.amdhsa_tg_split 0
		.amdhsa_exception_fp_ieee_invalid_op 0
		.amdhsa_exception_fp_denorm_src 0
		.amdhsa_exception_fp_ieee_div_zero 0
		.amdhsa_exception_fp_ieee_overflow 0
		.amdhsa_exception_fp_ieee_underflow 0
		.amdhsa_exception_fp_ieee_inexact 0
		.amdhsa_exception_int_div_zero 0
	.end_amdhsa_kernel

amdhsa.kernels:
  - .agpr_count:     0
    .args:
      - .offset:         0
        .size:           344
        .value_kind:     by_value
      - .offset:         344
        .size:           4
        .value_kind:     hidden_block_count_x
      - .offset:         348
        .size:           4
        .value_kind:     hidden_block_count_y
      - .offset:         352
        .size:           4
        .value_kind:     hidden_block_count_z
      - .offset:         356
        .size:           2
        .value_kind:     hidden_group_size_x
      - .offset:         358
        .size:           2
        .value_kind:     hidden_group_size_y
      - .offset:         360
        .size:           2
        .value_kind:     hidden_group_size_z
      - .offset:         362
        .size:           2
        .value_kind:     hidden_remainder_x
      - .offset:         364
        .size:           2
        .value_kind:     hidden_remainder_y
      - .offset:         366
        .size:           2
        .value_kind:     hidden_remainder_z
      - .offset:         384
        .size:           8
        .value_kind:     hidden_global_offset_x
      - .offset:         392
        .size:           8
        .value_kind:     hidden_global_offset_y
      - .offset:         400
        .size:           8
        .value_kind:     hidden_global_offset_z
      - .offset:         408
        .size:           2
        .value_kind:     hidden_grid_dims
      - .offset:         432
        .size:           8
        .value_kind:     hidden_multigrid_sync_arg
      - .offset:         464
        .size:           4
        .value_kind:     hidden_dynamic_lds_size
    .group_segment_fixed_size: 0
    .kernarg_segment_align: 8
    .kernarg_segment_size: 600
    .language:       OpenCL C
    .language_version:
      - 2
      - 0
    .max_flat_workgroup_size: 512
    .name:           _Z8yoco_fwd6Params
    .private_segment_fixed_size: 0
    .sgpr_count:     108
    .sgpr_spill_count: 27
    .symbol:         _Z8yoco_fwd6Params.kd
    .uniform_work_group_size: 1
    .uses_dynamic_stack: false
    .vgpr_count:     256
    .vgpr_spill_count: 0
    .wavefront_size: 64
